# v24 + the +kstep LDS-DMAs of five K-loops in saddr form via s[100:101]; no VALU address adds left in six K-loops
# speedup vs baseline: 1.0026x; 1.0009x over previous
.LBB0_677:
	ds_read_b128 v[156:159], v152
	ds_read_b128 v[160:163], v152 offset:1024
	ds_read_b128 v[164:167], v152 offset:2048
	ds_read_b128 v[168:171], v152 offset:3072
	ds_read_b128 v[172:175], v153
	ds_read_b128 v[176:179], v153 offset:1024
	ds_read_b128 v[180:183], v153 offset:2048
	ds_read_b128 v[184:187], v153 offset:3072
	s_add_u32 s0, s36, 0xfff00080
	s_addc_u32 s1, s37, -1
	s_cmp_eq_u32 s61, 60
	s_cselect_b32 s41, s56, s1
	s_cselect_b32 s40, s57, s0
	s_cselect_b32 s39, s15, s60
	s_cselect_b32 s38, s58, s59
	s_add_i32 m0, s31, 0xc000
	ds_read_b128 v[188:191], v154
	ds_read_b128 v[192:195], v154 offset:1024
	ds_read_b128 v[196:199], v154 offset:2048
	ds_read_b128 v[200:203], v154 offset:3072
	ds_read_b128 v[204:207], v154 offset:4096
	ds_read_b128 v[208:211], v154 offset:5120
	ds_read_b128 v[212:215], v154 offset:6144
	global_load_lds_dwordx4 v138, s[36:37]
	s_add_i32 m0, s31, 0xe000
	ds_read_b128 v[216:219], v154 offset:7168
	global_load_lds_dwordx4 v140, s[36:37]
	s_waitcnt vmcnt(8)
	s_waitcnt lgkmcnt(0)
	s_setprio 3
	s_barrier
	v_mfma_f32_16x16x32_bf16 v[124:127], v[156:159], v[188:191], v[124:127]
	v_mfma_f32_16x16x32_bf16 v[120:123], v[164:167], v[188:191], v[120:123]
	v_mfma_f32_16x16x32_bf16 v[108:111], v[156:159], v[196:199], v[108:111]
	v_mfma_f32_16x16x32_bf16 v[104:107], v[164:167], v[196:199], v[104:107]
	v_mfma_f32_16x16x32_bf16 v[92:95], v[156:159], v[204:207], v[92:95]
	v_mfma_f32_16x16x32_bf16 v[88:91], v[164:167], v[204:207], v[88:91]
	v_mfma_f32_16x16x32_bf16 v[76:79], v[156:159], v[212:215], v[76:79]
	v_mfma_f32_16x16x32_bf16 v[72:75], v[164:167], v[212:215], v[72:75]
	v_mfma_f32_16x16x32_bf16 v[124:127], v[160:163], v[192:195], v[124:127]
	v_mfma_f32_16x16x32_bf16 v[120:123], v[168:171], v[192:195], v[120:123]
	v_mfma_f32_16x16x32_bf16 v[108:111], v[160:163], v[200:203], v[108:111]
	v_mfma_f32_16x16x32_bf16 v[104:107], v[168:171], v[200:203], v[104:107]
	v_mfma_f32_16x16x32_bf16 v[92:95], v[160:163], v[208:211], v[92:95]
	v_mfma_f32_16x16x32_bf16 v[88:91], v[168:171], v[208:211], v[88:91]
	v_mfma_f32_16x16x32_bf16 v[76:79], v[160:163], v[216:219], v[76:79]
	v_mfma_f32_16x16x32_bf16 v[72:75], v[168:171], v[216:219], v[72:75]
	s_setprio 0
	s_setprio 3
	v_mfma_f32_16x16x32_bf16 v[116:119], v[172:175], v[188:191], v[116:119]
	v_mfma_f32_16x16x32_bf16 v[112:115], v[180:183], v[188:191], v[112:115]
	v_mfma_f32_16x16x32_bf16 v[100:103], v[172:175], v[196:199], v[100:103]
	v_mfma_f32_16x16x32_bf16 v[96:99], v[180:183], v[196:199], v[96:99]
	v_mfma_f32_16x16x32_bf16 v[84:87], v[172:175], v[204:207], v[84:87]
	v_mfma_f32_16x16x32_bf16 v[80:83], v[180:183], v[204:207], v[80:83]
	v_mfma_f32_16x16x32_bf16 v[68:71], v[172:175], v[212:215], v[68:71]
	v_mfma_f32_16x16x32_bf16 v[64:67], v[180:183], v[212:215], v[64:67]
	v_mfma_f32_16x16x32_bf16 v[116:119], v[176:179], v[192:195], v[116:119]
	v_mfma_f32_16x16x32_bf16 v[112:115], v[184:187], v[192:195], v[112:115]
	v_mfma_f32_16x16x32_bf16 v[100:103], v[176:179], v[200:203], v[100:103]
	v_mfma_f32_16x16x32_bf16 v[96:99], v[184:187], v[200:203], v[96:99]
	v_mfma_f32_16x16x32_bf16 v[84:87], v[176:179], v[208:211], v[84:87]
	v_mfma_f32_16x16x32_bf16 v[80:83], v[184:187], v[208:211], v[80:83]
	v_mfma_f32_16x16x32_bf16 v[68:71], v[176:179], v[216:219], v[68:71]
	v_mfma_f32_16x16x32_bf16 v[64:67], v[184:187], v[216:219], v[64:67]
	s_barrier
	s_setprio 0
	s_add_i32 s0, s51, s43
	s_mov_b32 m0, s0
	ds_read_b128 v[188:191], v154 offset:16384
	ds_read_b128 v[192:195], v154 offset:17408
	ds_read_b128 v[196:199], v154 offset:18432
	ds_read_b128 v[200:203], v154 offset:19456
	ds_read_b128 v[204:207], v154 offset:20480
	global_load_lds_dwordx4 v130, s[38:39]
	s_add_i32 m0, s0, 0x2000
	s_add_u32 s0, s38, 0x100000
	s_addc_u32 s1, s39, 0
	s_add_i32 s62, s52, s43
	global_load_lds_dwordx4 v134, s[38:39]
	s_mov_b32 m0, s62
	s_nop 0
	global_load_lds_dwordx4 v130, s[0:1]
	s_add_i32 m0, s62, 0x2000
	ds_read_b128 v[216:219], v154 offset:23552
	global_load_lds_dwordx4 v134, s[0:1]
	s_mov_b32 m0, s31
	ds_read_b128 v[212:215], v154 offset:22528
	global_load_lds_dwordx4 v128, s[40:41]
	s_mov_b32 m0, s35
	ds_read_b128 v[208:211], v154 offset:21504
	global_load_lds_dwordx4 v132, s[40:41]
	s_waitcnt vmcnt(8)
	s_waitcnt lgkmcnt(0)
	s_setprio 3
	s_barrier
	v_mfma_f32_16x16x32_bf16 v[60:63], v[156:159], v[188:191], v[60:63]
	v_mfma_f32_16x16x32_bf16 v[56:59], v[164:167], v[188:191], v[56:59]
	v_mfma_f32_16x16x32_bf16 v[44:47], v[156:159], v[196:199], v[44:47]
	v_mfma_f32_16x16x32_bf16 v[40:43], v[164:167], v[196:199], v[40:43]
	v_mfma_f32_16x16x32_bf16 v[28:31], v[156:159], v[204:207], v[28:31]
	v_mfma_f32_16x16x32_bf16 v[24:27], v[164:167], v[204:207], v[24:27]
	v_mfma_f32_16x16x32_bf16 v[12:15], v[156:159], v[212:215], v[12:15]
	v_mfma_f32_16x16x32_bf16 v[8:11], v[164:167], v[212:215], v[8:11]
	v_mfma_f32_16x16x32_bf16 v[60:63], v[160:163], v[192:195], v[60:63]
	v_mfma_f32_16x16x32_bf16 v[56:59], v[168:171], v[192:195], v[56:59]
	v_mfma_f32_16x16x32_bf16 v[44:47], v[160:163], v[200:203], v[44:47]
	v_mfma_f32_16x16x32_bf16 v[40:43], v[168:171], v[200:203], v[40:43]
	v_mfma_f32_16x16x32_bf16 v[28:31], v[160:163], v[208:211], v[28:31]
	v_mfma_f32_16x16x32_bf16 v[24:27], v[168:171], v[208:211], v[24:27]
	v_mfma_f32_16x16x32_bf16 v[12:15], v[160:163], v[216:219], v[12:15]
	v_mfma_f32_16x16x32_bf16 v[8:11], v[168:171], v[216:219], v[8:11]
	s_setprio 0
	s_setprio 3
	v_mfma_f32_16x16x32_bf16 v[52:55], v[172:175], v[188:191], v[52:55]
	v_mfma_f32_16x16x32_bf16 v[48:51], v[180:183], v[188:191], v[48:51]
	v_mfma_f32_16x16x32_bf16 v[36:39], v[172:175], v[196:199], v[36:39]
	v_mfma_f32_16x16x32_bf16 v[32:35], v[180:183], v[196:199], v[32:35]
	v_mfma_f32_16x16x32_bf16 v[20:23], v[172:175], v[204:207], v[20:23]
	v_mfma_f32_16x16x32_bf16 v[16:19], v[180:183], v[204:207], v[16:19]
	v_mfma_f32_16x16x32_bf16 v[4:7], v[172:175], v[212:215], v[4:7]
	v_mfma_f32_16x16x32_bf16 v[0:3], v[180:183], v[212:215], v[0:3]
	v_mfma_f32_16x16x32_bf16 v[52:55], v[176:179], v[192:195], v[52:55]
	v_mfma_f32_16x16x32_bf16 v[48:51], v[184:187], v[192:195], v[48:51]
	v_mfma_f32_16x16x32_bf16 v[36:39], v[176:179], v[200:203], v[36:39]
	v_mfma_f32_16x16x32_bf16 v[32:35], v[184:187], v[200:203], v[32:35]
	v_mfma_f32_16x16x32_bf16 v[20:23], v[176:179], v[208:211], v[20:23]
	v_mfma_f32_16x16x32_bf16 v[16:19], v[184:187], v[208:211], v[16:19]
	v_mfma_f32_16x16x32_bf16 v[4:7], v[176:179], v[216:219], v[4:7]
	v_mfma_f32_16x16x32_bf16 v[0:3], v[184:187], v[216:219], v[0:3]
	s_barrier
	s_setprio 0
	s_add_i32 s62, 0, 0x18000
	v_add_u32_e32 v155, s62, v149
	s_add_i32 s63, 0, 0x1c000
	ds_read_b128 v[156:159], v155
	ds_read_b128 v[160:163], v155 offset:1024
	ds_read_b128 v[164:167], v155 offset:2048
	ds_read_b128 v[168:171], v155 offset:3072
	v_add_u32_e32 v155, s63, v149
	ds_read_b128 v[172:175], v155
	ds_read_b128 v[176:179], v155 offset:1024
	ds_read_b128 v[180:183], v155 offset:2048
	ds_read_b128 v[184:187], v155 offset:3072
	s_add_u32 s0, s40, 0x100000
	s_addc_u32 s1, s41, 0
	s_mov_b32 m0, s44
	ds_read_b128 v[188:191], v154 offset:32768
	ds_read_b128 v[192:195], v154 offset:33792
	ds_read_b128 v[196:199], v154 offset:34816
	ds_read_b128 v[200:203], v154 offset:35840
	ds_read_b128 v[204:207], v154 offset:36864
	ds_read_b128 v[208:211], v154 offset:37888
	ds_read_b128 v[212:215], v154 offset:38912
	global_load_lds_dwordx4 v128, s[0:1]
	s_mov_b32 m0, s45
	ds_read_b128 v[216:219], v154 offset:39936
	global_load_lds_dwordx4 v132, s[0:1]
	s_waitcnt vmcnt(8)
	s_waitcnt lgkmcnt(0)
	s_setprio 3
	s_barrier
	v_mfma_f32_16x16x32_bf16 v[124:127], v[156:159], v[188:191], v[124:127]
	v_mfma_f32_16x16x32_bf16 v[120:123], v[164:167], v[188:191], v[120:123]
	v_mfma_f32_16x16x32_bf16 v[108:111], v[156:159], v[196:199], v[108:111]
	v_mfma_f32_16x16x32_bf16 v[104:107], v[164:167], v[196:199], v[104:107]
	v_mfma_f32_16x16x32_bf16 v[92:95], v[156:159], v[204:207], v[92:95]
	v_mfma_f32_16x16x32_bf16 v[88:91], v[164:167], v[204:207], v[88:91]
	v_mfma_f32_16x16x32_bf16 v[76:79], v[156:159], v[212:215], v[76:79]
	v_mfma_f32_16x16x32_bf16 v[72:75], v[164:167], v[212:215], v[72:75]
	v_mfma_f32_16x16x32_bf16 v[124:127], v[160:163], v[192:195], v[124:127]
	v_mfma_f32_16x16x32_bf16 v[120:123], v[168:171], v[192:195], v[120:123]
	v_mfma_f32_16x16x32_bf16 v[108:111], v[160:163], v[200:203], v[108:111]
	v_mfma_f32_16x16x32_bf16 v[104:107], v[168:171], v[200:203], v[104:107]
	v_mfma_f32_16x16x32_bf16 v[92:95], v[160:163], v[208:211], v[92:95]
	v_mfma_f32_16x16x32_bf16 v[88:91], v[168:171], v[208:211], v[88:91]
	v_mfma_f32_16x16x32_bf16 v[76:79], v[160:163], v[216:219], v[76:79]
	v_mfma_f32_16x16x32_bf16 v[72:75], v[168:171], v[216:219], v[72:75]
	s_setprio 0
	s_setprio 3
	v_mfma_f32_16x16x32_bf16 v[116:119], v[172:175], v[188:191], v[116:119]
	v_mfma_f32_16x16x32_bf16 v[112:115], v[180:183], v[188:191], v[112:115]
	v_mfma_f32_16x16x32_bf16 v[100:103], v[172:175], v[196:199], v[100:103]
	v_mfma_f32_16x16x32_bf16 v[96:99], v[180:183], v[196:199], v[96:99]
	v_mfma_f32_16x16x32_bf16 v[84:87], v[172:175], v[204:207], v[84:87]
	v_mfma_f32_16x16x32_bf16 v[80:83], v[180:183], v[204:207], v[80:83]
	v_mfma_f32_16x16x32_bf16 v[68:71], v[172:175], v[212:215], v[68:71]
	v_mfma_f32_16x16x32_bf16 v[64:67], v[180:183], v[212:215], v[64:67]
	v_mfma_f32_16x16x32_bf16 v[116:119], v[176:179], v[192:195], v[116:119]
	v_mfma_f32_16x16x32_bf16 v[112:115], v[184:187], v[192:195], v[112:115]
	v_mfma_f32_16x16x32_bf16 v[100:103], v[176:179], v[200:203], v[100:103]
	v_mfma_f32_16x16x32_bf16 v[96:99], v[184:187], v[200:203], v[96:99]
	v_mfma_f32_16x16x32_bf16 v[84:87], v[176:179], v[208:211], v[84:87]
	v_mfma_f32_16x16x32_bf16 v[80:83], v[184:187], v[208:211], v[80:83]
	v_mfma_f32_16x16x32_bf16 v[68:71], v[176:179], v[216:219], v[68:71]
	v_mfma_f32_16x16x32_bf16 v[64:67], v[184:187], v[216:219], v[64:67]
	s_barrier
	s_setprio 0
	s_add_i32 s0, s62, s43
	s_add_u32 s100, s38, 0x80
	s_addc_u32 s101, s39, 0
	s_mov_b32 m0, s0
	ds_read_b128 v[188:191], v154 offset:49152
	ds_read_b128 v[192:195], v154 offset:50176
	ds_read_b128 v[196:199], v154 offset:51200
	ds_read_b128 v[200:203], v154 offset:52224
	global_load_lds_dwordx4 v130, s[100:101]
	s_add_i32 m0, s0, 0x2000
	s_add_u32 s100, s38, 0x80
	s_addc_u32 s101, s39, 0
	s_add_u32 s0, s38, 0x100080
	s_addc_u32 s1, s39, 0
	s_add_i32 s38, s63, s43
	global_load_lds_dwordx4 v134, s[100:101]
	s_mov_b32 m0, s38
	ds_read_b128 v[216:219], v154 offset:56320
	global_load_lds_dwordx4 v130, s[0:1]
	s_add_i32 m0, s38, 0x2000
	ds_read_b128 v[212:215], v154 offset:55296
	global_load_lds_dwordx4 v134, s[0:1]
	s_add_u32 s100, s40, 0x80
	s_addc_u32 s101, s41, 0
	s_mov_b32 m0, s46
	ds_read_b128 v[208:211], v154 offset:54272
	global_load_lds_dwordx4 v128, s[100:101]
	s_add_u32 s100, s40, 0x80
	s_addc_u32 s101, s41, 0
	s_mov_b32 m0, s47
	ds_read_b128 v[204:207], v154 offset:53248
	global_load_lds_dwordx4 v132, s[100:101]
	s_waitcnt vmcnt(8)
	s_waitcnt lgkmcnt(0)
	s_setprio 3
	s_barrier
	v_mfma_f32_16x16x32_bf16 v[60:63], v[156:159], v[188:191], v[60:63]
	v_mfma_f32_16x16x32_bf16 v[56:59], v[164:167], v[188:191], v[56:59]
	v_mfma_f32_16x16x32_bf16 v[44:47], v[156:159], v[196:199], v[44:47]
	v_mfma_f32_16x16x32_bf16 v[40:43], v[164:167], v[196:199], v[40:43]
	v_mfma_f32_16x16x32_bf16 v[28:31], v[156:159], v[204:207], v[28:31]
	v_mfma_f32_16x16x32_bf16 v[24:27], v[164:167], v[204:207], v[24:27]
	v_mfma_f32_16x16x32_bf16 v[12:15], v[156:159], v[212:215], v[12:15]
	v_mfma_f32_16x16x32_bf16 v[8:11], v[164:167], v[212:215], v[8:11]
	v_mfma_f32_16x16x32_bf16 v[60:63], v[160:163], v[192:195], v[60:63]
	v_mfma_f32_16x16x32_bf16 v[56:59], v[168:171], v[192:195], v[56:59]
	v_mfma_f32_16x16x32_bf16 v[44:47], v[160:163], v[200:203], v[44:47]
	v_mfma_f32_16x16x32_bf16 v[40:43], v[168:171], v[200:203], v[40:43]
	v_mfma_f32_16x16x32_bf16 v[28:31], v[160:163], v[208:211], v[28:31]
	v_mfma_f32_16x16x32_bf16 v[24:27], v[168:171], v[208:211], v[24:27]
	v_mfma_f32_16x16x32_bf16 v[12:15], v[160:163], v[216:219], v[12:15]
	v_mfma_f32_16x16x32_bf16 v[8:11], v[168:171], v[216:219], v[8:11]
	s_setprio 0
	s_setprio 3
	v_mfma_f32_16x16x32_bf16 v[52:55], v[172:175], v[188:191], v[52:55]
	v_mfma_f32_16x16x32_bf16 v[48:51], v[180:183], v[188:191], v[48:51]
	v_mfma_f32_16x16x32_bf16 v[36:39], v[172:175], v[196:199], v[36:39]
	v_mfma_f32_16x16x32_bf16 v[32:35], v[180:183], v[196:199], v[32:35]
	v_mfma_f32_16x16x32_bf16 v[20:23], v[172:175], v[204:207], v[20:23]
	v_mfma_f32_16x16x32_bf16 v[16:19], v[180:183], v[204:207], v[16:19]
	v_mfma_f32_16x16x32_bf16 v[4:7], v[172:175], v[212:215], v[4:7]
	v_mfma_f32_16x16x32_bf16 v[0:3], v[180:183], v[212:215], v[0:3]
	v_mfma_f32_16x16x32_bf16 v[52:55], v[176:179], v[192:195], v[52:55]
	v_mfma_f32_16x16x32_bf16 v[48:51], v[184:187], v[192:195], v[48:51]
	v_mfma_f32_16x16x32_bf16 v[36:39], v[176:179], v[200:203], v[36:39]
	v_mfma_f32_16x16x32_bf16 v[32:35], v[184:187], v[200:203], v[32:35]
	v_mfma_f32_16x16x32_bf16 v[20:23], v[176:179], v[208:211], v[20:23]
	v_mfma_f32_16x16x32_bf16 v[16:19], v[184:187], v[208:211], v[16:19]
	v_mfma_f32_16x16x32_bf16 v[4:7], v[176:179], v[216:219], v[4:7]
	v_mfma_f32_16x16x32_bf16 v[0:3], v[184:187], v[216:219], v[0:3]
	s_barrier
	s_setprio 0
	s_add_u32 s36, s36, 0x100
	s_addc_u32 s37, s37, 0
	s_add_i32 s61, s61, 2
	s_add_u32 s59, s59, 0x100
	s_addc_u32 s60, s60, 0
	s_cmp_gt_u32 s61, 61
	s_cbranch_scc0 .LBB0_677
	s_and_b64 vcc, exec, s[12:13]
	s_cbranch_vccz .LBB0_680
	s_barrier

.LBB0_705:
	ds_read_b128 v[24:27], v191
	ds_read_b128 v[28:31], v191 offset:1024
	ds_read_b128 v[16:19], v191 offset:2048
	ds_read_b128 v[20:23], v191 offset:3072
	ds_read_b128 v[8:11], v192
	ds_read_b128 v[12:15], v192 offset:1024
	ds_read_b128 v[0:3], v192 offset:2048
	ds_read_b128 v[4:7], v192 offset:3072
	s_add_u32 s0, s44, 0xfff80080
	s_addc_u32 s1, s45, -1
	s_cmp_eq_u32 s70, 28
	s_cselect_b32 s49, s60, s1
	s_cselect_b32 s48, s66, s0
	s_cselect_b32 s47, s31, s69
	s_cselect_b32 s46, s67, s68
	s_add_i32 m0, s41, 0xc000
	ds_read_b128 v[178:181], v193
	ds_read_b128 v[182:185], v193 offset:1024
	ds_read_b128 v[194:197], v193 offset:2048
	ds_read_b128 v[198:201], v193 offset:3072
	ds_read_b128 v[208:211], v193 offset:4096
	ds_read_b128 v[212:215], v193 offset:5120
	ds_read_b128 v[216:219], v193 offset:6144
	global_load_lds_dwordx4 v170, s[44:45]
	s_add_i32 m0, s41, 0xe000
	ds_read_b128 v[220:223], v193 offset:7168
	global_load_lds_dwordx4 v172, s[44:45]
	s_waitcnt vmcnt(8)
	s_waitcnt lgkmcnt(0)
	s_setprio 3
	s_barrier
	v_mfma_scale_f32_16x16x128_f8f6f4 v[156:159], v[24:31], v[178:185], v[156:159], v186, v186 op_sel_hi:[0,0,0]
	v_mfma_scale_f32_16x16x128_f8f6f4 v[152:155], v[16:23], v[178:185], v[152:155], v186, v186 op_sel_hi:[0,0,0]
	v_mfma_scale_f32_16x16x128_f8f6f4 v[140:143], v[24:31], v[194:201], v[140:143], v186, v186 op_sel_hi:[0,0,0]
	v_mfma_scale_f32_16x16x128_f8f6f4 v[136:139], v[16:23], v[194:201], v[136:139], v186, v186 op_sel_hi:[0,0,0]
	v_mfma_scale_f32_16x16x128_f8f6f4 v[124:127], v[24:31], v[208:215], v[124:127], v186, v186 op_sel_hi:[0,0,0]
	v_mfma_scale_f32_16x16x128_f8f6f4 v[120:123], v[16:23], v[208:215], v[120:123], v186, v186 op_sel_hi:[0,0,0]
	v_mfma_scale_f32_16x16x128_f8f6f4 v[108:111], v[24:31], v[216:223], v[108:111], v186, v186 op_sel_hi:[0,0,0]
	v_mfma_scale_f32_16x16x128_f8f6f4 v[104:107], v[16:23], v[216:223], v[104:107], v186, v186 op_sel_hi:[0,0,0]
	s_setprio 0
	s_setprio 3
	v_mfma_scale_f32_16x16x128_f8f6f4 v[148:151], v[8:15], v[178:185], v[148:151], v186, v186 op_sel_hi:[0,0,0]
	v_mfma_scale_f32_16x16x128_f8f6f4 v[144:147], v[0:7], v[178:185], v[144:147], v186, v186 op_sel_hi:[0,0,0]
	v_mfma_scale_f32_16x16x128_f8f6f4 v[132:135], v[8:15], v[194:201], v[132:135], v186, v186 op_sel_hi:[0,0,0]
	v_mfma_scale_f32_16x16x128_f8f6f4 v[128:131], v[0:7], v[194:201], v[128:131], v186, v186 op_sel_hi:[0,0,0]
	v_mfma_scale_f32_16x16x128_f8f6f4 v[116:119], v[8:15], v[208:215], v[116:119], v186, v186 op_sel_hi:[0,0,0]
	v_mfma_scale_f32_16x16x128_f8f6f4 v[112:115], v[0:7], v[208:215], v[112:115], v186, v186 op_sel_hi:[0,0,0]
	v_mfma_scale_f32_16x16x128_f8f6f4 v[100:103], v[8:15], v[216:223], v[100:103], v186, v186 op_sel_hi:[0,0,0]
	v_mfma_scale_f32_16x16x128_f8f6f4 v[96:99], v[0:7], v[216:223], v[96:99], v186, v186 op_sel_hi:[0,0,0]
	s_barrier
	s_setprio 0
	s_add_i32 s0, s58, s51
	s_mov_b32 m0, s0
	ds_read_b128 v[194:197], v193 offset:16384
	ds_read_b128 v[198:201], v193 offset:17408
	ds_read_b128 v[208:211], v193 offset:18432
	ds_read_b128 v[212:215], v193 offset:19456
	ds_read_b128 v[216:219], v193 offset:20480
	global_load_lds_dwordx4 v162, s[46:47]
	s_add_i32 m0, s0, 0x2000
	s_add_u32 s0, s46, 0x80000
	s_addc_u32 s1, s47, 0
	s_add_i32 s71, s59, s51
	global_load_lds_dwordx4 v166, s[46:47]
	s_mov_b32 m0, s71
	s_nop 0
	global_load_lds_dwordx4 v162, s[0:1]
	s_add_i32 m0, s71, 0x2000
	ds_read_b128 v[228:231], v193 offset:23552
	global_load_lds_dwordx4 v166, s[0:1]
	s_mov_b32 m0, s41
	ds_read_b128 v[224:227], v193 offset:22528
	global_load_lds_dwordx4 v160, s[48:49]
	s_mov_b32 m0, s43
	ds_read_b128 v[220:223], v193 offset:21504
	global_load_lds_dwordx4 v164, s[48:49]
	s_waitcnt vmcnt(8)
	s_waitcnt lgkmcnt(0)
	s_setprio 3
	s_barrier
	v_mfma_scale_f32_16x16x128_f8f6f4 v[92:95], v[24:31], v[194:201], v[92:95], v186, v186 op_sel_hi:[0,0,0]
	v_mfma_scale_f32_16x16x128_f8f6f4 v[88:91], v[16:23], v[194:201], v[88:91], v186, v186 op_sel_hi:[0,0,0]
	v_mfma_scale_f32_16x16x128_f8f6f4 v[80:83], v[24:31], v[208:215], v[80:83], v186, v186 op_sel_hi:[0,0,0]
	v_mfma_scale_f32_16x16x128_f8f6f4 v[72:75], v[16:23], v[208:215], v[72:75], v186, v186 op_sel_hi:[0,0,0]
	v_mfma_scale_f32_16x16x128_f8f6f4 v[64:67], v[24:31], v[216:223], v[64:67], v186, v186 op_sel_hi:[0,0,0]
	v_mfma_scale_f32_16x16x128_f8f6f4 v[56:59], v[16:23], v[216:223], v[56:59], v186, v186 op_sel_hi:[0,0,0]
	v_mfma_scale_f32_16x16x128_f8f6f4 v[48:51], v[24:31], v[224:231], v[48:51], v186, v186 op_sel_hi:[0,0,0]
	v_mfma_scale_f32_16x16x128_f8f6f4 v[40:43], v[16:23], v[224:231], v[40:43], v186, v186 op_sel_hi:[0,0,0]
	s_setprio 0
	s_setprio 3
	v_mfma_scale_f32_16x16x128_f8f6f4 v[84:87], v[8:15], v[194:201], v[84:87], v186, v186 op_sel_hi:[0,0,0]
	v_mfma_scale_f32_16x16x128_f8f6f4 v[76:79], v[0:7], v[194:201], v[76:79], v186, v186 op_sel_hi:[0,0,0]
	v_mfma_scale_f32_16x16x128_f8f6f4 v[68:71], v[8:15], v[208:215], v[68:71], v186, v186 op_sel_hi:[0,0,0]
	v_mfma_scale_f32_16x16x128_f8f6f4 v[60:63], v[0:7], v[208:215], v[60:63], v186, v186 op_sel_hi:[0,0,0]
	v_mfma_scale_f32_16x16x128_f8f6f4 v[52:55], v[8:15], v[216:223], v[52:55], v186, v186 op_sel_hi:[0,0,0]
	v_mfma_scale_f32_16x16x128_f8f6f4 v[44:47], v[0:7], v[216:223], v[44:47], v186, v186 op_sel_hi:[0,0,0]
	v_mfma_scale_f32_16x16x128_f8f6f4 v[36:39], v[8:15], v[224:231], v[36:39], v186, v186 op_sel_hi:[0,0,0]
	v_mfma_scale_f32_16x16x128_f8f6f4 v[32:35], v[0:7], v[224:231], v[32:35], v186, v186 op_sel_hi:[0,0,0]
	s_barrier
	s_setprio 0
	s_add_i32 s71, 0, 0x18000
	s_add_i32 s73, 0, 0x1c000
	v_add_u32_e32 v12, s71, v188
	v_add_u32_e32 v28, s73, v188
	ds_read_b128 v[0:3], v12
	ds_read_b128 v[4:7], v12 offset:1024
	ds_read_b128 v[8:11], v12 offset:2048
	ds_read_b128 v[12:15], v12 offset:3072
	ds_read_b128 v[16:19], v28
	ds_read_b128 v[20:23], v28 offset:1024
	ds_read_b128 v[24:27], v28 offset:2048
	ds_read_b128 v[28:31], v28 offset:3072
	s_add_u32 s0, s48, 0x80000
	s_addc_u32 s1, s49, 0
	s_mov_b32 m0, s52
	ds_read_b128 v[194:197], v193 offset:32768
	ds_read_b128 v[198:201], v193 offset:33792
	ds_read_b128 v[208:211], v193 offset:34816
	ds_read_b128 v[212:215], v193 offset:35840
	ds_read_b128 v[216:219], v193 offset:36864
	ds_read_b128 v[220:223], v193 offset:37888
	ds_read_b128 v[224:227], v193 offset:38912
	global_load_lds_dwordx4 v160, s[0:1]
	s_mov_b32 m0, s53
	ds_read_b128 v[228:231], v193 offset:39936
	global_load_lds_dwordx4 v164, s[0:1]
	s_waitcnt vmcnt(8)
	s_waitcnt lgkmcnt(0)
	s_setprio 3
	s_barrier
	v_mfma_scale_f32_16x16x128_f8f6f4 v[156:159], v[0:7], v[194:201], v[156:159], v186, v186 op_sel_hi:[0,0,0]
	v_mfma_scale_f32_16x16x128_f8f6f4 v[152:155], v[8:15], v[194:201], v[152:155], v186, v186 op_sel_hi:[0,0,0]
	v_mfma_scale_f32_16x16x128_f8f6f4 v[140:143], v[0:7], v[208:215], v[140:143], v186, v186 op_sel_hi:[0,0,0]
	v_mfma_scale_f32_16x16x128_f8f6f4 v[136:139], v[8:15], v[208:215], v[136:139], v186, v186 op_sel_hi:[0,0,0]
	v_mfma_scale_f32_16x16x128_f8f6f4 v[124:127], v[0:7], v[216:223], v[124:127], v186, v186 op_sel_hi:[0,0,0]
	v_mfma_scale_f32_16x16x128_f8f6f4 v[120:123], v[8:15], v[216:223], v[120:123], v186, v186 op_sel_hi:[0,0,0]
	v_mfma_scale_f32_16x16x128_f8f6f4 v[108:111], v[0:7], v[224:231], v[108:111], v186, v186 op_sel_hi:[0,0,0]
	v_mfma_scale_f32_16x16x128_f8f6f4 v[104:107], v[8:15], v[224:231], v[104:107], v186, v186 op_sel_hi:[0,0,0]
	s_setprio 0
	s_setprio 3
	v_mfma_scale_f32_16x16x128_f8f6f4 v[148:151], v[16:23], v[194:201], v[148:151], v186, v186 op_sel_hi:[0,0,0]
	v_mfma_scale_f32_16x16x128_f8f6f4 v[144:147], v[24:31], v[194:201], v[144:147], v186, v186 op_sel_hi:[0,0,0]
	v_mfma_scale_f32_16x16x128_f8f6f4 v[132:135], v[16:23], v[208:215], v[132:135], v186, v186 op_sel_hi:[0,0,0]
	v_mfma_scale_f32_16x16x128_f8f6f4 v[128:131], v[24:31], v[208:215], v[128:131], v186, v186 op_sel_hi:[0,0,0]
	v_mfma_scale_f32_16x16x128_f8f6f4 v[116:119], v[16:23], v[216:223], v[116:119], v186, v186 op_sel_hi:[0,0,0]
	v_mfma_scale_f32_16x16x128_f8f6f4 v[112:115], v[24:31], v[216:223], v[112:115], v186, v186 op_sel_hi:[0,0,0]
	v_mfma_scale_f32_16x16x128_f8f6f4 v[100:103], v[16:23], v[224:231], v[100:103], v186, v186 op_sel_hi:[0,0,0]
	v_mfma_scale_f32_16x16x128_f8f6f4 v[96:99], v[24:31], v[224:231], v[96:99], v186, v186 op_sel_hi:[0,0,0]
	s_barrier
	s_setprio 0
	s_add_i32 s0, s71, s51
	s_add_u32 s100, s46, 0x80
	s_addc_u32 s101, s47, 0
	s_mov_b32 m0, s0
	ds_read_b128 v[194:197], v193 offset:49152
	ds_read_b128 v[198:201], v193 offset:50176
	ds_read_b128 v[208:211], v193 offset:51200
	ds_read_b128 v[212:215], v193 offset:52224
	global_load_lds_dwordx4 v162, s[100:101]
	s_add_i32 m0, s0, 0x2000
	s_add_u32 s100, s46, 0x80
	s_addc_u32 s101, s47, 0
	s_add_u32 s0, s46, 0x80080
	s_addc_u32 s1, s47, 0
	s_add_i32 s46, s73, s51
	global_load_lds_dwordx4 v166, s[100:101]
	s_mov_b32 m0, s46
	ds_read_b128 v[228:231], v193 offset:56320
	global_load_lds_dwordx4 v162, s[0:1]
	s_add_i32 m0, s46, 0x2000
	ds_read_b128 v[224:227], v193 offset:55296
	global_load_lds_dwordx4 v166, s[0:1]
	s_add_u32 s100, s48, 0x80
	s_addc_u32 s101, s49, 0
	s_mov_b32 m0, s55
	ds_read_b128 v[220:223], v193 offset:54272
	global_load_lds_dwordx4 v160, s[100:101]
	s_add_u32 s100, s48, 0x80
	s_addc_u32 s101, s49, 0
	s_mov_b32 m0, s56
	ds_read_b128 v[216:219], v193 offset:53248
	global_load_lds_dwordx4 v164, s[100:101]
	s_waitcnt vmcnt(8)
	s_waitcnt lgkmcnt(0)
	s_setprio 3
	s_barrier
	v_mfma_scale_f32_16x16x128_f8f6f4 v[92:95], v[0:7], v[194:201], v[92:95], v186, v186 op_sel_hi:[0,0,0]
	v_mfma_scale_f32_16x16x128_f8f6f4 v[88:91], v[8:15], v[194:201], v[88:91], v186, v186 op_sel_hi:[0,0,0]
	v_mfma_scale_f32_16x16x128_f8f6f4 v[80:83], v[0:7], v[208:215], v[80:83], v186, v186 op_sel_hi:[0,0,0]
	v_mfma_scale_f32_16x16x128_f8f6f4 v[72:75], v[8:15], v[208:215], v[72:75], v186, v186 op_sel_hi:[0,0,0]
	v_mfma_scale_f32_16x16x128_f8f6f4 v[64:67], v[0:7], v[216:223], v[64:67], v186, v186 op_sel_hi:[0,0,0]
	v_mfma_scale_f32_16x16x128_f8f6f4 v[56:59], v[8:15], v[216:223], v[56:59], v186, v186 op_sel_hi:[0,0,0]
	v_mfma_scale_f32_16x16x128_f8f6f4 v[48:51], v[0:7], v[224:231], v[48:51], v186, v186 op_sel_hi:[0,0,0]
	v_mfma_scale_f32_16x16x128_f8f6f4 v[40:43], v[8:15], v[224:231], v[40:43], v186, v186 op_sel_hi:[0,0,0]
	s_setprio 0
	s_setprio 3
	v_mfma_scale_f32_16x16x128_f8f6f4 v[84:87], v[16:23], v[194:201], v[84:87], v186, v186 op_sel_hi:[0,0,0]
	v_mfma_scale_f32_16x16x128_f8f6f4 v[76:79], v[24:31], v[194:201], v[76:79], v186, v186 op_sel_hi:[0,0,0]
	v_mfma_scale_f32_16x16x128_f8f6f4 v[68:71], v[16:23], v[208:215], v[68:71], v186, v186 op_sel_hi:[0,0,0]
	v_mfma_scale_f32_16x16x128_f8f6f4 v[60:63], v[24:31], v[208:215], v[60:63], v186, v186 op_sel_hi:[0,0,0]
	v_mfma_scale_f32_16x16x128_f8f6f4 v[52:55], v[16:23], v[216:223], v[52:55], v186, v186 op_sel_hi:[0,0,0]
	v_mfma_scale_f32_16x16x128_f8f6f4 v[44:47], v[24:31], v[216:223], v[44:47], v186, v186 op_sel_hi:[0,0,0]
	v_mfma_scale_f32_16x16x128_f8f6f4 v[36:39], v[16:23], v[224:231], v[36:39], v186, v186 op_sel_hi:[0,0,0]
	v_mfma_scale_f32_16x16x128_f8f6f4 v[32:35], v[24:31], v[224:231], v[32:35], v186, v186 op_sel_hi:[0,0,0]
	s_barrier
	s_setprio 0
	s_add_u32 s44, s44, 0x100
	s_addc_u32 s45, s45, 0
	s_add_i32 s70, s70, 2
	s_add_u32 s68, s68, 0x100
	s_addc_u32 s69, s69, 0
	s_cmp_gt_u32 s70, 29
	s_cbranch_scc0 .LBB0_705
	s_and_b64 vcc, exec, s[12:13]
	s_cbranch_vccz .LBB0_708
	s_barrier

.LBB0_1637:
	ds_read_b128 v[152:155], v149
	ds_read_b128 v[156:159], v149 offset:1024
	ds_read_b128 v[160:163], v149 offset:2048
	ds_read_b128 v[164:167], v149 offset:3072
	ds_read_b128 v[168:171], v150
	ds_read_b128 v[172:175], v150 offset:1024
	ds_read_b128 v[176:179], v150 offset:2048
	ds_read_b128 v[180:183], v150 offset:3072
	s_add_u32 s0, s42, 0xfff00080
	s_addc_u32 s1, s43, -1
	s_cmp_eq_u32 s68, 60
	s_cselect_b32 s47, s35, s1
	s_cselect_b32 s46, s64, s0
	s_cselect_b32 s45, s31, s67
	s_cselect_b32 s44, s65, s66
	s_add_i32 m0, s41, 0xc000
	ds_read_b128 v[184:187], v151
	ds_read_b128 v[188:191], v151 offset:1024
	ds_read_b128 v[192:195], v151 offset:2048
	ds_read_b128 v[196:199], v151 offset:3072
	ds_read_b128 v[200:203], v151 offset:4096
	ds_read_b128 v[210:213], v151 offset:5120
	ds_read_b128 v[214:217], v151 offset:6144
	global_load_lds_dwordx4 v136, s[42:43]
	s_add_i32 m0, s41, 0xe000
	ds_read_b128 v[218:221], v151 offset:7168
	global_load_lds_dwordx4 v138, s[42:43]
	s_waitcnt vmcnt(8)
	s_waitcnt lgkmcnt(0)
	s_setprio 3
	s_barrier
	v_mfma_f32_16x16x32_bf16 v[124:127], v[152:155], v[184:187], v[124:127]
	v_mfma_f32_16x16x32_bf16 v[120:123], v[160:163], v[184:187], v[120:123]
	v_mfma_f32_16x16x32_bf16 v[116:119], v[152:155], v[192:195], v[116:119]
	v_mfma_f32_16x16x32_bf16 v[108:111], v[160:163], v[192:195], v[108:111]
	v_mfma_f32_16x16x32_bf16 v[100:103], v[152:155], v[200:203], v[100:103]
	v_mfma_f32_16x16x32_bf16 v[92:95], v[160:163], v[200:203], v[92:95]
	v_mfma_f32_16x16x32_bf16 v[84:87], v[152:155], v[214:217], v[84:87]
	v_mfma_f32_16x16x32_bf16 v[76:79], v[160:163], v[214:217], v[76:79]
	v_mfma_f32_16x16x32_bf16 v[124:127], v[156:159], v[188:191], v[124:127]
	v_mfma_f32_16x16x32_bf16 v[120:123], v[164:167], v[188:191], v[120:123]
	v_mfma_f32_16x16x32_bf16 v[116:119], v[156:159], v[196:199], v[116:119]
	v_mfma_f32_16x16x32_bf16 v[108:111], v[164:167], v[196:199], v[108:111]
	v_mfma_f32_16x16x32_bf16 v[100:103], v[156:159], v[210:213], v[100:103]
	v_mfma_f32_16x16x32_bf16 v[92:95], v[164:167], v[210:213], v[92:95]
	v_mfma_f32_16x16x32_bf16 v[84:87], v[156:159], v[218:221], v[84:87]
	v_mfma_f32_16x16x32_bf16 v[76:79], v[164:167], v[218:221], v[76:79]
	s_setprio 0
	s_setprio 3
	v_mfma_f32_16x16x32_bf16 v[112:115], v[168:171], v[184:187], v[112:115]
	v_mfma_f32_16x16x32_bf16 v[104:107], v[176:179], v[184:187], v[104:107]
	v_mfma_f32_16x16x32_bf16 v[96:99], v[168:171], v[192:195], v[96:99]
	v_mfma_f32_16x16x32_bf16 v[88:91], v[176:179], v[192:195], v[88:91]
	v_mfma_f32_16x16x32_bf16 v[80:83], v[168:171], v[200:203], v[80:83]
	v_mfma_f32_16x16x32_bf16 v[72:75], v[176:179], v[200:203], v[72:75]
	v_mfma_f32_16x16x32_bf16 v[68:71], v[168:171], v[214:217], v[68:71]
	v_mfma_f32_16x16x32_bf16 v[64:67], v[176:179], v[214:217], v[64:67]
	v_mfma_f32_16x16x32_bf16 v[112:115], v[172:175], v[188:191], v[112:115]
	v_mfma_f32_16x16x32_bf16 v[104:107], v[180:183], v[188:191], v[104:107]
	v_mfma_f32_16x16x32_bf16 v[96:99], v[172:175], v[196:199], v[96:99]
	v_mfma_f32_16x16x32_bf16 v[88:91], v[180:183], v[196:199], v[88:91]
	v_mfma_f32_16x16x32_bf16 v[80:83], v[172:175], v[210:213], v[80:83]
	v_mfma_f32_16x16x32_bf16 v[72:75], v[180:183], v[210:213], v[72:75]
	v_mfma_f32_16x16x32_bf16 v[68:71], v[172:175], v[218:221], v[68:71]
	v_mfma_f32_16x16x32_bf16 v[64:67], v[180:183], v[218:221], v[64:67]
	s_barrier
	s_setprio 0
	s_add_i32 s0, s57, s49
	s_mov_b32 m0, s0
	ds_read_b128 v[184:187], v151 offset:16384
	ds_read_b128 v[188:191], v151 offset:17408
	ds_read_b128 v[192:195], v151 offset:18432
	ds_read_b128 v[196:199], v151 offset:19456
	ds_read_b128 v[200:203], v151 offset:20480
	global_load_lds_dwordx4 v130, s[44:45]
	s_add_i32 m0, s0, 0x2000
	s_add_u32 s0, s44, 0x100000
	s_addc_u32 s1, s45, 0
	s_add_i32 s69, s58, s49
	global_load_lds_dwordx4 v134, s[44:45]
	s_mov_b32 m0, s69
	s_nop 0
	global_load_lds_dwordx4 v130, s[0:1]
	s_add_i32 m0, s69, 0x2000
	ds_read_b128 v[218:221], v151 offset:23552
	global_load_lds_dwordx4 v134, s[0:1]
	s_mov_b32 m0, s41
	ds_read_b128 v[214:217], v151 offset:22528
	global_load_lds_dwordx4 v128, s[46:47]
	s_mov_b32 m0, s50
	ds_read_b128 v[210:213], v151 offset:21504
	global_load_lds_dwordx4 v132, s[46:47]
	s_waitcnt vmcnt(8)
	s_waitcnt lgkmcnt(0)
	s_setprio 3
	s_barrier
	v_mfma_f32_16x16x32_bf16 v[60:63], v[152:155], v[184:187], v[60:63]
	v_mfma_f32_16x16x32_bf16 v[56:59], v[160:163], v[184:187], v[56:59]
	v_mfma_f32_16x16x32_bf16 v[52:55], v[152:155], v[192:195], v[52:55]
	v_mfma_f32_16x16x32_bf16 v[44:47], v[160:163], v[192:195], v[44:47]
	v_mfma_f32_16x16x32_bf16 v[36:39], v[152:155], v[200:203], v[36:39]
	v_mfma_f32_16x16x32_bf16 v[28:31], v[160:163], v[200:203], v[28:31]
	v_mfma_f32_16x16x32_bf16 v[20:23], v[152:155], v[214:217], v[20:23]
	v_mfma_f32_16x16x32_bf16 v[12:15], v[160:163], v[214:217], v[12:15]
	v_mfma_f32_16x16x32_bf16 v[60:63], v[156:159], v[188:191], v[60:63]
	v_mfma_f32_16x16x32_bf16 v[56:59], v[164:167], v[188:191], v[56:59]
	v_mfma_f32_16x16x32_bf16 v[52:55], v[156:159], v[196:199], v[52:55]
	v_mfma_f32_16x16x32_bf16 v[44:47], v[164:167], v[196:199], v[44:47]
	v_mfma_f32_16x16x32_bf16 v[36:39], v[156:159], v[210:213], v[36:39]
	v_mfma_f32_16x16x32_bf16 v[28:31], v[164:167], v[210:213], v[28:31]
	v_mfma_f32_16x16x32_bf16 v[20:23], v[156:159], v[218:221], v[20:23]
	v_mfma_f32_16x16x32_bf16 v[12:15], v[164:167], v[218:221], v[12:15]
	s_setprio 0
	s_setprio 3
	v_mfma_f32_16x16x32_bf16 v[48:51], v[168:171], v[184:187], v[48:51]
	v_mfma_f32_16x16x32_bf16 v[40:43], v[176:179], v[184:187], v[40:43]
	v_mfma_f32_16x16x32_bf16 v[32:35], v[168:171], v[192:195], v[32:35]
	v_mfma_f32_16x16x32_bf16 v[24:27], v[176:179], v[192:195], v[24:27]
	v_mfma_f32_16x16x32_bf16 v[16:19], v[168:171], v[200:203], v[16:19]
	v_mfma_f32_16x16x32_bf16 v[8:11], v[176:179], v[200:203], v[8:11]
	v_mfma_f32_16x16x32_bf16 v[4:7], v[168:171], v[214:217], v[4:7]
	v_mfma_f32_16x16x32_bf16 v[0:3], v[176:179], v[214:217], v[0:3]
	v_mfma_f32_16x16x32_bf16 v[48:51], v[172:175], v[188:191], v[48:51]
	v_mfma_f32_16x16x32_bf16 v[40:43], v[180:183], v[188:191], v[40:43]
	v_mfma_f32_16x16x32_bf16 v[32:35], v[172:175], v[196:199], v[32:35]
	v_mfma_f32_16x16x32_bf16 v[24:27], v[180:183], v[196:199], v[24:27]
	v_mfma_f32_16x16x32_bf16 v[16:19], v[172:175], v[210:213], v[16:19]
	v_mfma_f32_16x16x32_bf16 v[8:11], v[180:183], v[210:213], v[8:11]
	v_mfma_f32_16x16x32_bf16 v[4:7], v[172:175], v[218:221], v[4:7]
	v_mfma_f32_16x16x32_bf16 v[0:3], v[180:183], v[218:221], v[0:3]
	s_barrier
	s_setprio 0
	s_add_i32 s69, 0, 0x18000
	s_add_i32 s70, 0, 0x1c000
	v_add_u32_e32 v164, s69, v147
	v_add_u32_e32 v180, s70, v147
	ds_read_b128 v[152:155], v164
	ds_read_b128 v[156:159], v164 offset:1024
	ds_read_b128 v[160:163], v164 offset:2048
	ds_read_b128 v[164:167], v164 offset:3072
	ds_read_b128 v[168:171], v180
	ds_read_b128 v[172:175], v180 offset:1024
	ds_read_b128 v[176:179], v180 offset:2048
	ds_read_b128 v[180:183], v180 offset:3072
	s_add_u32 s0, s46, 0x100000
	s_addc_u32 s1, s47, 0
	s_mov_b32 m0, s51
	ds_read_b128 v[184:187], v151 offset:32768
	ds_read_b128 v[188:191], v151 offset:33792
	ds_read_b128 v[192:195], v151 offset:34816
	ds_read_b128 v[196:199], v151 offset:35840
	ds_read_b128 v[200:203], v151 offset:36864
	ds_read_b128 v[210:213], v151 offset:37888
	ds_read_b128 v[214:217], v151 offset:38912
	global_load_lds_dwordx4 v128, s[0:1]
	s_mov_b32 m0, s52
	ds_read_b128 v[218:221], v151 offset:39936
	global_load_lds_dwordx4 v132, s[0:1]
	s_waitcnt vmcnt(8)
	s_waitcnt lgkmcnt(0)
	s_setprio 3
	s_barrier
	v_mfma_f32_16x16x32_bf16 v[124:127], v[152:155], v[184:187], v[124:127]
	v_mfma_f32_16x16x32_bf16 v[120:123], v[160:163], v[184:187], v[120:123]
	v_mfma_f32_16x16x32_bf16 v[116:119], v[152:155], v[192:195], v[116:119]
	v_mfma_f32_16x16x32_bf16 v[108:111], v[160:163], v[192:195], v[108:111]
	v_mfma_f32_16x16x32_bf16 v[100:103], v[152:155], v[200:203], v[100:103]
	v_mfma_f32_16x16x32_bf16 v[92:95], v[160:163], v[200:203], v[92:95]
	v_mfma_f32_16x16x32_bf16 v[84:87], v[152:155], v[214:217], v[84:87]
	v_mfma_f32_16x16x32_bf16 v[76:79], v[160:163], v[214:217], v[76:79]
	v_mfma_f32_16x16x32_bf16 v[124:127], v[156:159], v[188:191], v[124:127]
	v_mfma_f32_16x16x32_bf16 v[120:123], v[164:167], v[188:191], v[120:123]
	v_mfma_f32_16x16x32_bf16 v[116:119], v[156:159], v[196:199], v[116:119]
	v_mfma_f32_16x16x32_bf16 v[108:111], v[164:167], v[196:199], v[108:111]
	v_mfma_f32_16x16x32_bf16 v[100:103], v[156:159], v[210:213], v[100:103]
	v_mfma_f32_16x16x32_bf16 v[92:95], v[164:167], v[210:213], v[92:95]
	v_mfma_f32_16x16x32_bf16 v[84:87], v[156:159], v[218:221], v[84:87]
	v_mfma_f32_16x16x32_bf16 v[76:79], v[164:167], v[218:221], v[76:79]
	s_setprio 0
	s_setprio 3
	v_mfma_f32_16x16x32_bf16 v[112:115], v[168:171], v[184:187], v[112:115]
	v_mfma_f32_16x16x32_bf16 v[104:107], v[176:179], v[184:187], v[104:107]
	v_mfma_f32_16x16x32_bf16 v[96:99], v[168:171], v[192:195], v[96:99]
	v_mfma_f32_16x16x32_bf16 v[88:91], v[176:179], v[192:195], v[88:91]
	v_mfma_f32_16x16x32_bf16 v[80:83], v[168:171], v[200:203], v[80:83]
	v_mfma_f32_16x16x32_bf16 v[72:75], v[176:179], v[200:203], v[72:75]
	v_mfma_f32_16x16x32_bf16 v[68:71], v[168:171], v[214:217], v[68:71]
	v_mfma_f32_16x16x32_bf16 v[64:67], v[176:179], v[214:217], v[64:67]
	v_mfma_f32_16x16x32_bf16 v[112:115], v[172:175], v[188:191], v[112:115]
	v_mfma_f32_16x16x32_bf16 v[104:107], v[180:183], v[188:191], v[104:107]
	v_mfma_f32_16x16x32_bf16 v[96:99], v[172:175], v[196:199], v[96:99]
	v_mfma_f32_16x16x32_bf16 v[88:91], v[180:183], v[196:199], v[88:91]
	v_mfma_f32_16x16x32_bf16 v[80:83], v[172:175], v[210:213], v[80:83]
	v_mfma_f32_16x16x32_bf16 v[72:75], v[180:183], v[210:213], v[72:75]
	v_mfma_f32_16x16x32_bf16 v[68:71], v[172:175], v[218:221], v[68:71]
	v_mfma_f32_16x16x32_bf16 v[64:67], v[180:183], v[218:221], v[64:67]
	s_barrier
	s_setprio 0
	s_add_i32 s0, s69, s49
	s_add_u32 s100, s44, 0x80
	s_addc_u32 s101, s45, 0
	s_mov_b32 m0, s0
	ds_read_b128 v[184:187], v151 offset:49152
	ds_read_b128 v[188:191], v151 offset:50176
	ds_read_b128 v[192:195], v151 offset:51200
	ds_read_b128 v[196:199], v151 offset:52224
	global_load_lds_dwordx4 v130, s[100:101]
	s_add_i32 m0, s0, 0x2000
	s_add_u32 s100, s44, 0x80
	s_addc_u32 s101, s45, 0
	s_add_u32 s0, s44, 0x100080
	s_addc_u32 s1, s45, 0
	s_add_i32 s44, s70, s49
	global_load_lds_dwordx4 v134, s[100:101]
	s_mov_b32 m0, s44
	ds_read_b128 v[218:221], v151 offset:56320
	global_load_lds_dwordx4 v130, s[0:1]
	s_add_i32 m0, s44, 0x2000
	ds_read_b128 v[214:217], v151 offset:55296
	global_load_lds_dwordx4 v134, s[0:1]
	s_add_u32 s100, s46, 0x80
	s_addc_u32 s101, s47, 0
	s_mov_b32 m0, s54
	ds_read_b128 v[210:213], v151 offset:54272
	global_load_lds_dwordx4 v128, s[100:101]
	s_add_u32 s100, s46, 0x80
	s_addc_u32 s101, s47, 0
	s_mov_b32 m0, s55
	ds_read_b128 v[200:203], v151 offset:53248
	global_load_lds_dwordx4 v132, s[100:101]
	s_waitcnt vmcnt(8)
	s_waitcnt lgkmcnt(0)
	s_setprio 3
	s_barrier
	v_mfma_f32_16x16x32_bf16 v[60:63], v[152:155], v[184:187], v[60:63]
	v_mfma_f32_16x16x32_bf16 v[56:59], v[160:163], v[184:187], v[56:59]
	v_mfma_f32_16x16x32_bf16 v[52:55], v[152:155], v[192:195], v[52:55]
	v_mfma_f32_16x16x32_bf16 v[44:47], v[160:163], v[192:195], v[44:47]
	v_mfma_f32_16x16x32_bf16 v[36:39], v[152:155], v[200:203], v[36:39]
	v_mfma_f32_16x16x32_bf16 v[28:31], v[160:163], v[200:203], v[28:31]
	v_mfma_f32_16x16x32_bf16 v[20:23], v[152:155], v[214:217], v[20:23]
	v_mfma_f32_16x16x32_bf16 v[12:15], v[160:163], v[214:217], v[12:15]
	v_mfma_f32_16x16x32_bf16 v[60:63], v[156:159], v[188:191], v[60:63]
	v_mfma_f32_16x16x32_bf16 v[56:59], v[164:167], v[188:191], v[56:59]
	v_mfma_f32_16x16x32_bf16 v[52:55], v[156:159], v[196:199], v[52:55]
	v_mfma_f32_16x16x32_bf16 v[44:47], v[164:167], v[196:199], v[44:47]
	v_mfma_f32_16x16x32_bf16 v[36:39], v[156:159], v[210:213], v[36:39]
	v_mfma_f32_16x16x32_bf16 v[28:31], v[164:167], v[210:213], v[28:31]
	v_mfma_f32_16x16x32_bf16 v[20:23], v[156:159], v[218:221], v[20:23]
	v_mfma_f32_16x16x32_bf16 v[12:15], v[164:167], v[218:221], v[12:15]
	s_setprio 0
	s_setprio 3
	v_mfma_f32_16x16x32_bf16 v[48:51], v[168:171], v[184:187], v[48:51]
	v_mfma_f32_16x16x32_bf16 v[40:43], v[176:179], v[184:187], v[40:43]
	v_mfma_f32_16x16x32_bf16 v[32:35], v[168:171], v[192:195], v[32:35]
	v_mfma_f32_16x16x32_bf16 v[24:27], v[176:179], v[192:195], v[24:27]
	v_mfma_f32_16x16x32_bf16 v[16:19], v[168:171], v[200:203], v[16:19]
	v_mfma_f32_16x16x32_bf16 v[8:11], v[176:179], v[200:203], v[8:11]
	v_mfma_f32_16x16x32_bf16 v[4:7], v[168:171], v[214:217], v[4:7]
	v_mfma_f32_16x16x32_bf16 v[0:3], v[176:179], v[214:217], v[0:3]
	v_mfma_f32_16x16x32_bf16 v[48:51], v[172:175], v[188:191], v[48:51]
	v_mfma_f32_16x16x32_bf16 v[40:43], v[180:183], v[188:191], v[40:43]
	v_mfma_f32_16x16x32_bf16 v[32:35], v[172:175], v[196:199], v[32:35]
	v_mfma_f32_16x16x32_bf16 v[24:27], v[180:183], v[196:199], v[24:27]
	v_mfma_f32_16x16x32_bf16 v[16:19], v[172:175], v[210:213], v[16:19]
	v_mfma_f32_16x16x32_bf16 v[8:11], v[180:183], v[210:213], v[8:11]
	v_mfma_f32_16x16x32_bf16 v[4:7], v[172:175], v[218:221], v[4:7]
	v_mfma_f32_16x16x32_bf16 v[0:3], v[180:183], v[218:221], v[0:3]
	s_barrier
	s_setprio 0
	s_add_u32 s42, s42, 0x100
	s_addc_u32 s43, s43, 0
	s_add_i32 s68, s68, 2
	s_add_u32 s66, s66, 0x100
	s_addc_u32 s67, s67, 0
	s_cmp_gt_u32 s68, 61
	s_cbranch_scc0 .LBB0_1637
	s_and_b64 vcc, exec, s[16:17]
	s_cbranch_vccz .LBB0_1640
	s_barrier

.LBB0_1813:
	ds_read_b128 v[148:151], v156
	ds_read_b128 v[160:163], v156 offset:1024
	ds_read_b128 v[164:167], v156 offset:2048
	ds_read_b128 v[168:171], v156 offset:3072
	ds_read_b128 v[172:175], v157
	ds_read_b128 v[176:179], v157 offset:1024
	ds_read_b128 v[180:183], v157 offset:2048
	ds_read_b128 v[184:187], v157 offset:3072
	s_add_u32 s0, s36, 0xfff00080
	s_addc_u32 s1, s37, -1
	s_cmp_eq_u32 s64, 60
	s_cselect_b32 s41, s59, s1
	s_cselect_b32 s40, s60, s0
	s_cselect_b32 s39, s17, s63
	s_cselect_b32 s38, s61, s62
	s_add_i32 m0, s31, 0xc000
	ds_read_b128 v[188:191], v158
	ds_read_b128 v[192:195], v158 offset:1024
	ds_read_b128 v[196:199], v158 offset:2048
	ds_read_b128 v[200:203], v158 offset:3072
	ds_read_b128 v[210:213], v158 offset:4096
	ds_read_b128 v[214:217], v158 offset:5120
	ds_read_b128 v[218:221], v158 offset:6144
	global_load_lds_dwordx4 v140, s[36:37]
	s_add_i32 m0, s31, 0xe000
	ds_read_b128 v[222:225], v158 offset:7168
	global_load_lds_dwordx4 v142, s[36:37]
	s_waitcnt vmcnt(8)
	s_waitcnt lgkmcnt(0)
	s_setprio 3
	s_barrier
	v_mfma_f32_16x16x32_bf16 v[124:127], v[148:151], v[188:191], v[124:127]
	v_mfma_f32_16x16x32_bf16 v[120:123], v[164:167], v[188:191], v[120:123]
	v_mfma_f32_16x16x32_bf16 v[108:111], v[148:151], v[196:199], v[108:111]
	v_mfma_f32_16x16x32_bf16 v[104:107], v[164:167], v[196:199], v[104:107]
	v_mfma_f32_16x16x32_bf16 v[92:95], v[148:151], v[210:213], v[92:95]
	v_mfma_f32_16x16x32_bf16 v[88:91], v[164:167], v[210:213], v[88:91]
	v_mfma_f32_16x16x32_bf16 v[76:79], v[148:151], v[218:221], v[76:79]
	v_mfma_f32_16x16x32_bf16 v[72:75], v[164:167], v[218:221], v[72:75]
	v_mfma_f32_16x16x32_bf16 v[124:127], v[160:163], v[192:195], v[124:127]
	v_mfma_f32_16x16x32_bf16 v[120:123], v[168:171], v[192:195], v[120:123]
	v_mfma_f32_16x16x32_bf16 v[108:111], v[160:163], v[200:203], v[108:111]
	v_mfma_f32_16x16x32_bf16 v[104:107], v[168:171], v[200:203], v[104:107]
	v_mfma_f32_16x16x32_bf16 v[92:95], v[160:163], v[214:217], v[92:95]
	v_mfma_f32_16x16x32_bf16 v[88:91], v[168:171], v[214:217], v[88:91]
	v_mfma_f32_16x16x32_bf16 v[76:79], v[160:163], v[222:225], v[76:79]
	v_mfma_f32_16x16x32_bf16 v[72:75], v[168:171], v[222:225], v[72:75]
	s_setprio 0
	s_setprio 3
	v_mfma_f32_16x16x32_bf16 v[116:119], v[172:175], v[188:191], v[116:119]
	v_mfma_f32_16x16x32_bf16 v[112:115], v[180:183], v[188:191], v[112:115]
	v_mfma_f32_16x16x32_bf16 v[100:103], v[172:175], v[196:199], v[100:103]
	v_mfma_f32_16x16x32_bf16 v[96:99], v[180:183], v[196:199], v[96:99]
	v_mfma_f32_16x16x32_bf16 v[84:87], v[172:175], v[210:213], v[84:87]
	v_mfma_f32_16x16x32_bf16 v[80:83], v[180:183], v[210:213], v[80:83]
	v_mfma_f32_16x16x32_bf16 v[68:71], v[172:175], v[218:221], v[68:71]
	v_mfma_f32_16x16x32_bf16 v[64:67], v[180:183], v[218:221], v[64:67]
	v_mfma_f32_16x16x32_bf16 v[116:119], v[176:179], v[192:195], v[116:119]
	v_mfma_f32_16x16x32_bf16 v[112:115], v[184:187], v[192:195], v[112:115]
	v_mfma_f32_16x16x32_bf16 v[100:103], v[176:179], v[200:203], v[100:103]
	v_mfma_f32_16x16x32_bf16 v[96:99], v[184:187], v[200:203], v[96:99]
	v_mfma_f32_16x16x32_bf16 v[84:87], v[176:179], v[214:217], v[84:87]
	v_mfma_f32_16x16x32_bf16 v[80:83], v[184:187], v[214:217], v[80:83]
	v_mfma_f32_16x16x32_bf16 v[68:71], v[176:179], v[222:225], v[68:71]
	v_mfma_f32_16x16x32_bf16 v[64:67], v[184:187], v[222:225], v[64:67]
	s_barrier
	s_setprio 0
	s_add_i32 s0, s52, s43
	s_mov_b32 m0, s0
	ds_read_b128 v[188:191], v158 offset:16384
	ds_read_b128 v[192:195], v158 offset:17408
	ds_read_b128 v[196:199], v158 offset:18432
	ds_read_b128 v[200:203], v158 offset:19456
	ds_read_b128 v[210:213], v158 offset:20480
	global_load_lds_dwordx4 v132, s[38:39]
	s_add_i32 m0, s0, 0x2000
	s_add_u32 s0, s38, 0x100000
	s_addc_u32 s1, s39, 0
	s_add_i32 s65, s53, s43
	global_load_lds_dwordx4 v136, s[38:39]
	s_mov_b32 m0, s65
	s_nop 0
	global_load_lds_dwordx4 v132, s[0:1]
	s_add_i32 m0, s65, 0x2000
	ds_read_b128 v[222:225], v158 offset:23552
	global_load_lds_dwordx4 v136, s[0:1]
	s_mov_b32 m0, s31
	ds_read_b128 v[218:221], v158 offset:22528
	global_load_lds_dwordx4 v130, s[40:41]
	s_mov_b32 m0, s35
	ds_read_b128 v[214:217], v158 offset:21504
	global_load_lds_dwordx4 v134, s[40:41]
	s_waitcnt vmcnt(8)
	s_waitcnt lgkmcnt(0)
	s_setprio 3
	s_barrier
	v_mfma_f32_16x16x32_bf16 v[60:63], v[148:151], v[188:191], v[60:63]
	v_mfma_f32_16x16x32_bf16 v[56:59], v[164:167], v[188:191], v[56:59]
	v_mfma_f32_16x16x32_bf16 v[44:47], v[148:151], v[196:199], v[44:47]
	v_mfma_f32_16x16x32_bf16 v[40:43], v[164:167], v[196:199], v[40:43]
	v_mfma_f32_16x16x32_bf16 v[28:31], v[148:151], v[210:213], v[28:31]
	v_mfma_f32_16x16x32_bf16 v[24:27], v[164:167], v[210:213], v[24:27]
	v_mfma_f32_16x16x32_bf16 v[12:15], v[148:151], v[218:221], v[12:15]
	v_mfma_f32_16x16x32_bf16 v[8:11], v[164:167], v[218:221], v[8:11]
	v_mfma_f32_16x16x32_bf16 v[60:63], v[160:163], v[192:195], v[60:63]
	v_mfma_f32_16x16x32_bf16 v[56:59], v[168:171], v[192:195], v[56:59]
	v_mfma_f32_16x16x32_bf16 v[44:47], v[160:163], v[200:203], v[44:47]
	v_mfma_f32_16x16x32_bf16 v[40:43], v[168:171], v[200:203], v[40:43]
	v_mfma_f32_16x16x32_bf16 v[28:31], v[160:163], v[214:217], v[28:31]
	v_mfma_f32_16x16x32_bf16 v[24:27], v[168:171], v[214:217], v[24:27]
	v_mfma_f32_16x16x32_bf16 v[12:15], v[160:163], v[222:225], v[12:15]
	v_mfma_f32_16x16x32_bf16 v[8:11], v[168:171], v[222:225], v[8:11]
	s_setprio 0
	s_setprio 3
	v_mfma_f32_16x16x32_bf16 v[52:55], v[172:175], v[188:191], v[52:55]
	v_mfma_f32_16x16x32_bf16 v[48:51], v[180:183], v[188:191], v[48:51]
	v_mfma_f32_16x16x32_bf16 v[36:39], v[172:175], v[196:199], v[36:39]
	v_mfma_f32_16x16x32_bf16 v[32:35], v[180:183], v[196:199], v[32:35]
	v_mfma_f32_16x16x32_bf16 v[20:23], v[172:175], v[210:213], v[20:23]
	v_mfma_f32_16x16x32_bf16 v[16:19], v[180:183], v[210:213], v[16:19]
	v_mfma_f32_16x16x32_bf16 v[4:7], v[172:175], v[218:221], v[4:7]
	v_mfma_f32_16x16x32_bf16 v[0:3], v[180:183], v[218:221], v[0:3]
	v_mfma_f32_16x16x32_bf16 v[52:55], v[176:179], v[192:195], v[52:55]
	v_mfma_f32_16x16x32_bf16 v[48:51], v[184:187], v[192:195], v[48:51]
	v_mfma_f32_16x16x32_bf16 v[36:39], v[176:179], v[200:203], v[36:39]
	v_mfma_f32_16x16x32_bf16 v[32:35], v[184:187], v[200:203], v[32:35]
	v_mfma_f32_16x16x32_bf16 v[20:23], v[176:179], v[214:217], v[20:23]
	v_mfma_f32_16x16x32_bf16 v[16:19], v[184:187], v[214:217], v[16:19]
	v_mfma_f32_16x16x32_bf16 v[4:7], v[176:179], v[222:225], v[4:7]
	v_mfma_f32_16x16x32_bf16 v[0:3], v[184:187], v[222:225], v[0:3]
	s_barrier
	s_setprio 0
	s_add_i32 s65, 0, 0x18000
	v_add_u32_e32 v128, s65, v153
	s_add_i32 s66, 0, 0x1c000
	ds_read_b128 v[148:151], v128
	ds_read_b128 v[160:163], v128 offset:1024
	ds_read_b128 v[164:167], v128 offset:2048
	ds_read_b128 v[168:171], v128 offset:3072
	v_add_u32_e32 v128, s66, v153
	ds_read_b128 v[172:175], v128
	ds_read_b128 v[176:179], v128 offset:1024
	ds_read_b128 v[180:183], v128 offset:2048
	ds_read_b128 v[184:187], v128 offset:3072
	s_add_u32 s0, s40, 0x100000
	s_addc_u32 s1, s41, 0
	s_mov_b32 m0, s44
	ds_read_b128 v[188:191], v158 offset:32768
	ds_read_b128 v[192:195], v158 offset:33792
	ds_read_b128 v[196:199], v158 offset:34816
	ds_read_b128 v[200:203], v158 offset:35840
	ds_read_b128 v[210:213], v158 offset:36864
	ds_read_b128 v[214:217], v158 offset:37888
	ds_read_b128 v[218:221], v158 offset:38912
	global_load_lds_dwordx4 v130, s[0:1]
	s_mov_b32 m0, s45
	ds_read_b128 v[222:225], v158 offset:39936
	global_load_lds_dwordx4 v134, s[0:1]
	s_waitcnt vmcnt(8)
	s_waitcnt lgkmcnt(0)
	s_setprio 3
	s_barrier
	v_mfma_f32_16x16x32_bf16 v[124:127], v[148:151], v[188:191], v[124:127]
	v_mfma_f32_16x16x32_bf16 v[120:123], v[164:167], v[188:191], v[120:123]
	v_mfma_f32_16x16x32_bf16 v[108:111], v[148:151], v[196:199], v[108:111]
	v_mfma_f32_16x16x32_bf16 v[104:107], v[164:167], v[196:199], v[104:107]
	v_mfma_f32_16x16x32_bf16 v[92:95], v[148:151], v[210:213], v[92:95]
	v_mfma_f32_16x16x32_bf16 v[88:91], v[164:167], v[210:213], v[88:91]
	v_mfma_f32_16x16x32_bf16 v[76:79], v[148:151], v[218:221], v[76:79]
	v_mfma_f32_16x16x32_bf16 v[72:75], v[164:167], v[218:221], v[72:75]
	v_mfma_f32_16x16x32_bf16 v[124:127], v[160:163], v[192:195], v[124:127]
	v_mfma_f32_16x16x32_bf16 v[120:123], v[168:171], v[192:195], v[120:123]
	v_mfma_f32_16x16x32_bf16 v[108:111], v[160:163], v[200:203], v[108:111]
	v_mfma_f32_16x16x32_bf16 v[104:107], v[168:171], v[200:203], v[104:107]
	v_mfma_f32_16x16x32_bf16 v[92:95], v[160:163], v[214:217], v[92:95]
	v_mfma_f32_16x16x32_bf16 v[88:91], v[168:171], v[214:217], v[88:91]
	v_mfma_f32_16x16x32_bf16 v[76:79], v[160:163], v[222:225], v[76:79]
	v_mfma_f32_16x16x32_bf16 v[72:75], v[168:171], v[222:225], v[72:75]
	s_setprio 0
	s_setprio 3
	v_mfma_f32_16x16x32_bf16 v[116:119], v[172:175], v[188:191], v[116:119]
	v_mfma_f32_16x16x32_bf16 v[112:115], v[180:183], v[188:191], v[112:115]
	v_mfma_f32_16x16x32_bf16 v[100:103], v[172:175], v[196:199], v[100:103]
	v_mfma_f32_16x16x32_bf16 v[96:99], v[180:183], v[196:199], v[96:99]
	v_mfma_f32_16x16x32_bf16 v[84:87], v[172:175], v[210:213], v[84:87]
	v_mfma_f32_16x16x32_bf16 v[80:83], v[180:183], v[210:213], v[80:83]
	v_mfma_f32_16x16x32_bf16 v[68:71], v[172:175], v[218:221], v[68:71]
	v_mfma_f32_16x16x32_bf16 v[64:67], v[180:183], v[218:221], v[64:67]
	v_mfma_f32_16x16x32_bf16 v[116:119], v[176:179], v[192:195], v[116:119]
	v_mfma_f32_16x16x32_bf16 v[112:115], v[184:187], v[192:195], v[112:115]
	v_mfma_f32_16x16x32_bf16 v[100:103], v[176:179], v[200:203], v[100:103]
	v_mfma_f32_16x16x32_bf16 v[96:99], v[184:187], v[200:203], v[96:99]
	v_mfma_f32_16x16x32_bf16 v[84:87], v[176:179], v[214:217], v[84:87]
	v_mfma_f32_16x16x32_bf16 v[80:83], v[184:187], v[214:217], v[80:83]
	v_mfma_f32_16x16x32_bf16 v[68:71], v[176:179], v[222:225], v[68:71]
	v_mfma_f32_16x16x32_bf16 v[64:67], v[184:187], v[222:225], v[64:67]
	s_barrier
	s_setprio 0
	s_add_i32 s0, s65, s43
	s_add_u32 s100, s38, 0x80
	s_addc_u32 s101, s39, 0
	s_mov_b32 m0, s0
	ds_read_b128 v[188:191], v158 offset:49152
	ds_read_b128 v[192:195], v158 offset:50176
	ds_read_b128 v[196:199], v158 offset:51200
	ds_read_b128 v[200:203], v158 offset:52224
	global_load_lds_dwordx4 v132, s[100:101]
	s_add_i32 m0, s0, 0x2000
	s_add_u32 s100, s38, 0x80
	s_addc_u32 s101, s39, 0
	s_add_u32 s0, s38, 0x100080
	s_addc_u32 s1, s39, 0
	s_add_i32 s38, s66, s43
	global_load_lds_dwordx4 v136, s[100:101]
	s_mov_b32 m0, s38
	ds_read_b128 v[222:225], v158 offset:56320
	global_load_lds_dwordx4 v132, s[0:1]
	s_add_i32 m0, s38, 0x2000
	ds_read_b128 v[218:221], v158 offset:55296
	global_load_lds_dwordx4 v136, s[0:1]
	s_add_u32 s100, s40, 0x80
	s_addc_u32 s101, s41, 0
	s_mov_b32 m0, s49
	ds_read_b128 v[214:217], v158 offset:54272
	global_load_lds_dwordx4 v130, s[100:101]
	s_add_u32 s100, s40, 0x80
	s_addc_u32 s101, s41, 0
	s_mov_b32 m0, s50
	ds_read_b128 v[210:213], v158 offset:53248
	global_load_lds_dwordx4 v134, s[100:101]
	s_waitcnt vmcnt(8)
	s_waitcnt lgkmcnt(0)
	s_setprio 3
	s_barrier
	v_mfma_f32_16x16x32_bf16 v[60:63], v[148:151], v[188:191], v[60:63]
	v_mfma_f32_16x16x32_bf16 v[56:59], v[164:167], v[188:191], v[56:59]
	v_mfma_f32_16x16x32_bf16 v[44:47], v[148:151], v[196:199], v[44:47]
	v_mfma_f32_16x16x32_bf16 v[40:43], v[164:167], v[196:199], v[40:43]
	v_mfma_f32_16x16x32_bf16 v[28:31], v[148:151], v[210:213], v[28:31]
	v_mfma_f32_16x16x32_bf16 v[24:27], v[164:167], v[210:213], v[24:27]
	v_mfma_f32_16x16x32_bf16 v[12:15], v[148:151], v[218:221], v[12:15]
	v_mfma_f32_16x16x32_bf16 v[8:11], v[164:167], v[218:221], v[8:11]
	v_mfma_f32_16x16x32_bf16 v[60:63], v[160:163], v[192:195], v[60:63]
	v_mfma_f32_16x16x32_bf16 v[56:59], v[168:171], v[192:195], v[56:59]
	v_mfma_f32_16x16x32_bf16 v[44:47], v[160:163], v[200:203], v[44:47]
	v_mfma_f32_16x16x32_bf16 v[40:43], v[168:171], v[200:203], v[40:43]
	v_mfma_f32_16x16x32_bf16 v[28:31], v[160:163], v[214:217], v[28:31]
	v_mfma_f32_16x16x32_bf16 v[24:27], v[168:171], v[214:217], v[24:27]
	v_mfma_f32_16x16x32_bf16 v[12:15], v[160:163], v[222:225], v[12:15]
	v_mfma_f32_16x16x32_bf16 v[8:11], v[168:171], v[222:225], v[8:11]
	s_setprio 0
	s_setprio 3
	v_mfma_f32_16x16x32_bf16 v[52:55], v[172:175], v[188:191], v[52:55]
	v_mfma_f32_16x16x32_bf16 v[48:51], v[180:183], v[188:191], v[48:51]
	v_mfma_f32_16x16x32_bf16 v[36:39], v[172:175], v[196:199], v[36:39]
	v_mfma_f32_16x16x32_bf16 v[32:35], v[180:183], v[196:199], v[32:35]
	v_mfma_f32_16x16x32_bf16 v[20:23], v[172:175], v[210:213], v[20:23]
	v_mfma_f32_16x16x32_bf16 v[16:19], v[180:183], v[210:213], v[16:19]
	v_mfma_f32_16x16x32_bf16 v[4:7], v[172:175], v[218:221], v[4:7]
	v_mfma_f32_16x16x32_bf16 v[0:3], v[180:183], v[218:221], v[0:3]
	v_mfma_f32_16x16x32_bf16 v[52:55], v[176:179], v[192:195], v[52:55]
	v_mfma_f32_16x16x32_bf16 v[48:51], v[184:187], v[192:195], v[48:51]
	v_mfma_f32_16x16x32_bf16 v[36:39], v[176:179], v[200:203], v[36:39]
	v_mfma_f32_16x16x32_bf16 v[32:35], v[184:187], v[200:203], v[32:35]
	v_mfma_f32_16x16x32_bf16 v[20:23], v[176:179], v[214:217], v[20:23]
	v_mfma_f32_16x16x32_bf16 v[16:19], v[184:187], v[214:217], v[16:19]
	v_mfma_f32_16x16x32_bf16 v[4:7], v[176:179], v[222:225], v[4:7]
	v_mfma_f32_16x16x32_bf16 v[0:3], v[184:187], v[222:225], v[0:3]
	s_barrier
	s_setprio 0
	s_add_u32 s36, s36, 0x100
	s_addc_u32 s37, s37, 0
	s_add_i32 s64, s64, 2
	s_add_u32 s62, s62, 0x100
	s_addc_u32 s63, s63, 0
	s_cmp_gt_u32 s64, 61
	s_cbranch_scc0 .LBB0_1813
	s_and_b64 vcc, exec, s[14:15]
	s_cbranch_vccz .LBB0_1816
	s_barrier

.LBB0_1833:
	ds_read_b128 v[24:27], v193
	ds_read_b128 v[28:31], v193 offset:1024
	ds_read_b128 v[16:19], v193 offset:2048
	ds_read_b128 v[20:23], v193 offset:3072
	ds_read_b128 v[8:11], v194
	ds_read_b128 v[12:15], v194 offset:1024
	ds_read_b128 v[0:3], v194 offset:2048
	ds_read_b128 v[4:7], v194 offset:3072
	s_add_u32 s0, s36, 0xfff80080
	s_addc_u32 s1, s37, -1
	s_cmp_eq_u32 s65, 28
	s_cselect_b32 s41, s26, s1
	s_cselect_b32 s40, s27, s0
	s_cselect_b32 s39, s17, s64
	s_cselect_b32 s38, s31, s63
	s_add_i32 m0, s35, 0xc000
	ds_read_b128 v[180:183], v195
	ds_read_b128 v[184:187], v195 offset:1024
	ds_read_b128 v[210:213], v195 offset:2048
	ds_read_b128 v[214:217], v195 offset:3072
	ds_read_b128 v[218:221], v195 offset:4096
	ds_read_b128 v[222:225], v195 offset:5120
	ds_read_b128 v[226:229], v195 offset:6144
	global_load_lds_dwordx4 v172, s[36:37]
	s_add_i32 m0, s35, 0xe000
	ds_read_b128 v[230:233], v195 offset:7168
	global_load_lds_dwordx4 v174, s[36:37]
	s_waitcnt vmcnt(8)
	s_waitcnt lgkmcnt(0)
	s_setprio 3
	s_barrier
	v_mfma_scale_f32_16x16x128_f8f6f4 v[152:155], v[24:31], v[180:187], v[152:155], v188, v188 op_sel_hi:[0,0,0]
	v_mfma_scale_f32_16x16x128_f8f6f4 v[148:151], v[16:23], v[180:187], v[148:151], v188, v188 op_sel_hi:[0,0,0]
	v_mfma_scale_f32_16x16x128_f8f6f4 v[140:143], v[24:31], v[210:217], v[140:143], v188, v188 op_sel_hi:[0,0,0]
	v_mfma_scale_f32_16x16x128_f8f6f4 v[132:135], v[16:23], v[210:217], v[132:135], v188, v188 op_sel_hi:[0,0,0]
	v_mfma_scale_f32_16x16x128_f8f6f4 v[124:127], v[24:31], v[218:225], v[124:127], v188, v188 op_sel_hi:[0,0,0]
	v_mfma_scale_f32_16x16x128_f8f6f4 v[120:123], v[16:23], v[218:225], v[120:123], v188, v188 op_sel_hi:[0,0,0]
	v_mfma_scale_f32_16x16x128_f8f6f4 v[108:111], v[24:31], v[226:233], v[108:111], v188, v188 op_sel_hi:[0,0,0]
	v_mfma_scale_f32_16x16x128_f8f6f4 v[100:103], v[16:23], v[226:233], v[100:103], v188, v188 op_sel_hi:[0,0,0]
	s_setprio 0
	s_setprio 3
	v_mfma_scale_f32_16x16x128_f8f6f4 v[156:159], v[8:15], v[180:187], v[156:159], v188, v188 op_sel_hi:[0,0,0]
	v_mfma_scale_f32_16x16x128_f8f6f4 v[144:147], v[0:7], v[180:187], v[144:147], v188, v188 op_sel_hi:[0,0,0]
	v_mfma_scale_f32_16x16x128_f8f6f4 v[136:139], v[8:15], v[210:217], v[136:139], v188, v188 op_sel_hi:[0,0,0]
	v_mfma_scale_f32_16x16x128_f8f6f4 v[128:131], v[0:7], v[210:217], v[128:131], v188, v188 op_sel_hi:[0,0,0]
	v_mfma_scale_f32_16x16x128_f8f6f4 v[116:119], v[8:15], v[218:225], v[116:119], v188, v188 op_sel_hi:[0,0,0]
	v_mfma_scale_f32_16x16x128_f8f6f4 v[112:115], v[0:7], v[218:225], v[112:115], v188, v188 op_sel_hi:[0,0,0]
	v_mfma_scale_f32_16x16x128_f8f6f4 v[104:107], v[8:15], v[226:233], v[104:107], v188, v188 op_sel_hi:[0,0,0]
	v_mfma_scale_f32_16x16x128_f8f6f4 v[96:99], v[0:7], v[226:233], v[96:99], v188, v188 op_sel_hi:[0,0,0]
	s_barrier
	s_setprio 0
	s_add_i32 s0, s56, s45
	s_mov_b32 m0, s0
	ds_read_b128 v[210:213], v195 offset:16384
	ds_read_b128 v[214:217], v195 offset:17408
	ds_read_b128 v[218:221], v195 offset:18432
	ds_read_b128 v[222:225], v195 offset:19456
	ds_read_b128 v[226:229], v195 offset:20480
	global_load_lds_dwordx4 v164, s[38:39]
	s_add_i32 m0, s0, 0x2000
	s_add_u32 s0, s38, 0x80000
	s_addc_u32 s1, s39, 0
	s_add_i32 s66, s57, s45
	global_load_lds_dwordx4 v168, s[38:39]
	s_mov_b32 m0, s66
	s_nop 0
	global_load_lds_dwordx4 v164, s[0:1]
	s_add_i32 m0, s66, 0x2000
	ds_read_b128 v[238:241], v195 offset:23552
	global_load_lds_dwordx4 v168, s[0:1]
	s_mov_b32 m0, s35
	ds_read_b128 v[234:237], v195 offset:22528
	global_load_lds_dwordx4 v162, s[40:41]
	s_mov_b32 m0, s46
	ds_read_b128 v[230:233], v195 offset:21504
	global_load_lds_dwordx4 v166, s[40:41]
	s_waitcnt vmcnt(8)
	s_waitcnt lgkmcnt(0)
	s_setprio 3
	s_barrier
	v_mfma_scale_f32_16x16x128_f8f6f4 v[92:95], v[24:31], v[210:217], v[92:95], v188, v188 op_sel_hi:[0,0,0]
	v_mfma_scale_f32_16x16x128_f8f6f4 v[88:91], v[16:23], v[210:217], v[88:91], v188, v188 op_sel_hi:[0,0,0]
	v_mfma_scale_f32_16x16x128_f8f6f4 v[76:79], v[24:31], v[218:225], v[76:79], v188, v188 op_sel_hi:[0,0,0]
	v_mfma_scale_f32_16x16x128_f8f6f4 v[68:71], v[16:23], v[218:225], v[68:71], v188, v188 op_sel_hi:[0,0,0]
	v_mfma_scale_f32_16x16x128_f8f6f4 v[60:63], v[24:31], v[226:233], v[60:63], v188, v188 op_sel_hi:[0,0,0]
	v_mfma_scale_f32_16x16x128_f8f6f4 v[56:59], v[16:23], v[226:233], v[56:59], v188, v188 op_sel_hi:[0,0,0]
	v_mfma_scale_f32_16x16x128_f8f6f4 v[44:47], v[24:31], v[234:241], v[44:47], v188, v188 op_sel_hi:[0,0,0]
	v_mfma_scale_f32_16x16x128_f8f6f4 v[40:43], v[16:23], v[234:241], v[40:43], v188, v188 op_sel_hi:[0,0,0]
	s_setprio 0
	s_setprio 3
	v_mfma_scale_f32_16x16x128_f8f6f4 v[84:87], v[8:15], v[210:217], v[84:87], v188, v188 op_sel_hi:[0,0,0]
	v_mfma_scale_f32_16x16x128_f8f6f4 v[80:83], v[0:7], v[210:217], v[80:83], v188, v188 op_sel_hi:[0,0,0]
	v_mfma_scale_f32_16x16x128_f8f6f4 v[72:75], v[8:15], v[218:225], v[72:75], v188, v188 op_sel_hi:[0,0,0]
	v_mfma_scale_f32_16x16x128_f8f6f4 v[64:67], v[0:7], v[218:225], v[64:67], v188, v188 op_sel_hi:[0,0,0]
	v_mfma_scale_f32_16x16x128_f8f6f4 v[52:55], v[8:15], v[226:233], v[52:55], v188, v188 op_sel_hi:[0,0,0]
	v_mfma_scale_f32_16x16x128_f8f6f4 v[48:51], v[0:7], v[226:233], v[48:51], v188, v188 op_sel_hi:[0,0,0]
	v_mfma_scale_f32_16x16x128_f8f6f4 v[36:39], v[8:15], v[234:241], v[36:39], v188, v188 op_sel_hi:[0,0,0]
	v_mfma_scale_f32_16x16x128_f8f6f4 v[32:35], v[0:7], v[234:241], v[32:35], v188, v188 op_sel_hi:[0,0,0]
	s_barrier
	s_setprio 0
	s_add_i32 s66, 0, 0x18000
	s_add_i32 s67, 0, 0x1c000
	v_add_u32_e32 v12, s66, v190
	v_add_u32_e32 v28, s67, v190
	ds_read_b128 v[0:3], v12
	ds_read_b128 v[4:7], v12 offset:1024
	ds_read_b128 v[8:11], v12 offset:2048
	ds_read_b128 v[12:15], v12 offset:3072
	ds_read_b128 v[16:19], v28
	ds_read_b128 v[20:23], v28 offset:1024
	ds_read_b128 v[24:27], v28 offset:2048
	ds_read_b128 v[28:31], v28 offset:3072
	s_add_u32 s0, s40, 0x80000
	s_addc_u32 s1, s41, 0
	s_mov_b32 m0, s47
	ds_read_b128 v[210:213], v195 offset:32768
	ds_read_b128 v[214:217], v195 offset:33792
	ds_read_b128 v[218:221], v195 offset:34816
	ds_read_b128 v[222:225], v195 offset:35840
	ds_read_b128 v[226:229], v195 offset:36864
	ds_read_b128 v[230:233], v195 offset:37888
	ds_read_b128 v[234:237], v195 offset:38912
	global_load_lds_dwordx4 v162, s[0:1]
	s_mov_b32 m0, s48
	ds_read_b128 v[238:241], v195 offset:39936
	global_load_lds_dwordx4 v166, s[0:1]
	s_waitcnt vmcnt(8)
	s_waitcnt lgkmcnt(0)
	s_setprio 3
	s_barrier
	v_mfma_scale_f32_16x16x128_f8f6f4 v[152:155], v[0:7], v[210:217], v[152:155], v188, v188 op_sel_hi:[0,0,0]
	v_mfma_scale_f32_16x16x128_f8f6f4 v[148:151], v[8:15], v[210:217], v[148:151], v188, v188 op_sel_hi:[0,0,0]
	v_mfma_scale_f32_16x16x128_f8f6f4 v[140:143], v[0:7], v[218:225], v[140:143], v188, v188 op_sel_hi:[0,0,0]
	v_mfma_scale_f32_16x16x128_f8f6f4 v[132:135], v[8:15], v[218:225], v[132:135], v188, v188 op_sel_hi:[0,0,0]
	v_mfma_scale_f32_16x16x128_f8f6f4 v[124:127], v[0:7], v[226:233], v[124:127], v188, v188 op_sel_hi:[0,0,0]
	v_mfma_scale_f32_16x16x128_f8f6f4 v[120:123], v[8:15], v[226:233], v[120:123], v188, v188 op_sel_hi:[0,0,0]
	v_mfma_scale_f32_16x16x128_f8f6f4 v[108:111], v[0:7], v[234:241], v[108:111], v188, v188 op_sel_hi:[0,0,0]
	v_mfma_scale_f32_16x16x128_f8f6f4 v[100:103], v[8:15], v[234:241], v[100:103], v188, v188 op_sel_hi:[0,0,0]
	s_setprio 0
	s_setprio 3
	v_mfma_scale_f32_16x16x128_f8f6f4 v[156:159], v[16:23], v[210:217], v[156:159], v188, v188 op_sel_hi:[0,0,0]
	v_mfma_scale_f32_16x16x128_f8f6f4 v[144:147], v[24:31], v[210:217], v[144:147], v188, v188 op_sel_hi:[0,0,0]
	v_mfma_scale_f32_16x16x128_f8f6f4 v[136:139], v[16:23], v[218:225], v[136:139], v188, v188 op_sel_hi:[0,0,0]
	v_mfma_scale_f32_16x16x128_f8f6f4 v[128:131], v[24:31], v[218:225], v[128:131], v188, v188 op_sel_hi:[0,0,0]
	v_mfma_scale_f32_16x16x128_f8f6f4 v[116:119], v[16:23], v[226:233], v[116:119], v188, v188 op_sel_hi:[0,0,0]
	v_mfma_scale_f32_16x16x128_f8f6f4 v[112:115], v[24:31], v[226:233], v[112:115], v188, v188 op_sel_hi:[0,0,0]
	v_mfma_scale_f32_16x16x128_f8f6f4 v[104:107], v[16:23], v[234:241], v[104:107], v188, v188 op_sel_hi:[0,0,0]
	v_mfma_scale_f32_16x16x128_f8f6f4 v[96:99], v[24:31], v[234:241], v[96:99], v188, v188 op_sel_hi:[0,0,0]
	s_barrier
	s_setprio 0
	s_add_i32 s0, s66, s45
	s_add_u32 s100, s38, 0x80
	s_addc_u32 s101, s39, 0
	s_mov_b32 m0, s0
	ds_read_b128 v[210:213], v195 offset:49152
	ds_read_b128 v[214:217], v195 offset:50176
	ds_read_b128 v[218:221], v195 offset:51200
	ds_read_b128 v[222:225], v195 offset:52224
	global_load_lds_dwordx4 v164, s[100:101]
	s_add_i32 m0, s0, 0x2000
	s_add_u32 s100, s38, 0x80
	s_addc_u32 s101, s39, 0
	s_add_u32 s0, s38, 0x80080
	s_addc_u32 s1, s39, 0
	s_add_i32 s38, s67, s45
	global_load_lds_dwordx4 v168, s[100:101]
	s_mov_b32 m0, s38
	ds_read_b128 v[238:241], v195 offset:56320
	global_load_lds_dwordx4 v164, s[0:1]
	s_add_i32 m0, s38, 0x2000
	ds_read_b128 v[234:237], v195 offset:55296
	global_load_lds_dwordx4 v168, s[0:1]
	s_add_u32 s100, s40, 0x80
	s_addc_u32 s101, s41, 0
	s_mov_b32 m0, s51
	ds_read_b128 v[230:233], v195 offset:54272
	global_load_lds_dwordx4 v162, s[100:101]
	s_add_u32 s100, s40, 0x80
	s_addc_u32 s101, s41, 0
	s_mov_b32 m0, s52
	ds_read_b128 v[226:229], v195 offset:53248
	global_load_lds_dwordx4 v166, s[100:101]
	s_waitcnt vmcnt(8)
	s_waitcnt lgkmcnt(0)
	s_setprio 3
	s_barrier
	v_mfma_scale_f32_16x16x128_f8f6f4 v[92:95], v[0:7], v[210:217], v[92:95], v188, v188 op_sel_hi:[0,0,0]
	v_mfma_scale_f32_16x16x128_f8f6f4 v[88:91], v[8:15], v[210:217], v[88:91], v188, v188 op_sel_hi:[0,0,0]
	v_mfma_scale_f32_16x16x128_f8f6f4 v[76:79], v[0:7], v[218:225], v[76:79], v188, v188 op_sel_hi:[0,0,0]
	v_mfma_scale_f32_16x16x128_f8f6f4 v[68:71], v[8:15], v[218:225], v[68:71], v188, v188 op_sel_hi:[0,0,0]
	v_mfma_scale_f32_16x16x128_f8f6f4 v[60:63], v[0:7], v[226:233], v[60:63], v188, v188 op_sel_hi:[0,0,0]
	v_mfma_scale_f32_16x16x128_f8f6f4 v[56:59], v[8:15], v[226:233], v[56:59], v188, v188 op_sel_hi:[0,0,0]
	v_mfma_scale_f32_16x16x128_f8f6f4 v[44:47], v[0:7], v[234:241], v[44:47], v188, v188 op_sel_hi:[0,0,0]
	v_mfma_scale_f32_16x16x128_f8f6f4 v[40:43], v[8:15], v[234:241], v[40:43], v188, v188 op_sel_hi:[0,0,0]
	s_setprio 0
	s_setprio 3
	v_mfma_scale_f32_16x16x128_f8f6f4 v[84:87], v[16:23], v[210:217], v[84:87], v188, v188 op_sel_hi:[0,0,0]
	v_mfma_scale_f32_16x16x128_f8f6f4 v[80:83], v[24:31], v[210:217], v[80:83], v188, v188 op_sel_hi:[0,0,0]
	v_mfma_scale_f32_16x16x128_f8f6f4 v[72:75], v[16:23], v[218:225], v[72:75], v188, v188 op_sel_hi:[0,0,0]
	v_mfma_scale_f32_16x16x128_f8f6f4 v[64:67], v[24:31], v[218:225], v[64:67], v188, v188 op_sel_hi:[0,0,0]
	v_mfma_scale_f32_16x16x128_f8f6f4 v[52:55], v[16:23], v[226:233], v[52:55], v188, v188 op_sel_hi:[0,0,0]
	v_mfma_scale_f32_16x16x128_f8f6f4 v[48:51], v[24:31], v[226:233], v[48:51], v188, v188 op_sel_hi:[0,0,0]
	v_mfma_scale_f32_16x16x128_f8f6f4 v[36:39], v[16:23], v[234:241], v[36:39], v188, v188 op_sel_hi:[0,0,0]
	v_mfma_scale_f32_16x16x128_f8f6f4 v[32:35], v[24:31], v[234:241], v[32:35], v188, v188 op_sel_hi:[0,0,0]
	s_barrier
	s_setprio 0
	s_add_u32 s36, s36, 0x100
	s_addc_u32 s37, s37, 0
	s_add_i32 s65, s65, 2
	s_add_u32 s63, s63, 0x100
	s_addc_u32 s64, s64, 0
	s_cmp_gt_u32 s65, 29
	s_cbranch_scc0 .LBB0_1833
	s_and_b64 vcc, exec, s[14:15]
	s_cbranch_vccz .LBB0_1836
	s_barrier
